# code placement: one unexecuted 4-byte s_nop after the attention region so the down/proj GEMM loops and later code move by 4 bytes (same instructions as v162)
# baseline (speedup 1.0000x reference)
.LBB0_727:
	s_or_b64 exec, exec, s[16:17]
	s_and_saveexec_b64 s[16:17], s[8:9]
	s_cbranch_execz .LBB0_672
	v_lshlrev_b32_e32 v110, 16, v231
	s_waitcnt lgkmcnt(1)
	v_and_b32_e32 v111, 0xffff0000, v231
	s_waitcnt lgkmcnt(0)
	v_pk_mul_f32 v[112:113], v[172:173], v[110:111]
	v_pk_mul_f32 v[110:111], v[172:173], v[110:111] op_sel:[1,0] op_sel_hi:[0,1]
	v_sub_f32_e32 v112, v112, v113
	v_add_f32_e32 v110, v110, v111
	v_cvt_pk_bf16_f32 v112, v112, v110
	v_lshlrev_b64 v[110:111], 6, v[170:171]
	v_lshl_add_u64 v[110:111], v[164:165], 0, v[110:111]
	global_store_dword v[110:111], v112, off
	s_branch .LBB0_672
	s_nop 0
